# combo23 + scan stage A: LDS fragment reads double-buffered, tile t+1 reads issued before tile t MFMAs
# speedup vs baseline: 1.0044x; 1.0013x over previous
; #define LAS __attribute__((address_space(3)))
; __device__ __forceinline__ f32x4 mfma16(const bf16x8& a, const bf16x8& b, const f32x4& c) { return __builtin_amdgcn_mfma_f32_16x16x32_bf16(a, b, c, 0, 0, 0); }
; #define SC_UG(chs) do { const bf16_t* U_ = (const bf16_t*)(p.ws + WS_UT) + (size_t)(chs) * 8192; const float* G_ = (const float*)(p.ws + WS_GB) + (size_t)(chs) * 64; \
;         _Pragma("unroll") for (int tt = 0; tt < 4; ++tt) { u4n[tt] = *(const bf16x4*)(U_ + dv * 64 + 16 * tt + 4 * fq); g4n[tt] = *(const f32x4*)(G_ + 16 * tt + 4 * fq); } \
;         Gln = G_[63]; } while (0)
; template <bool PROMPT>
; __device__ __forceinline__ void scan_block(const Params& p, LAS unsigned char* lds, int chs0, int nsteps, const float* s0, float* sfin, int rowbase, int ntok, int h, int half) {
;     ...
;     for (int n = 0; n < nsteps; ++n) {
;         bf16x4 u4[4]; f32x4 g4[4]; const float Glc = Gln;
; #pragma unroll
;         for (int tt = 0; tt < 4; ++tt) { u4[tt] = u4n[tt]; g4[tt] = g4n[tt]; }
;         if constexpr (PROMPT) { const int c = (n + 1 < nsteps) ? n + 1 : nsteps - 1; SC_UG(chs0 + c); }
;         __builtin_amdgcn_sched_barrier(0);
;         const LAS unsigned char* B = lds + (n & 1) * SC_BUF;
;         bf16x8 Sb[4];
; #pragma unroll
;         for (int P = 0; P < 4; ++P) Sb[P] = pack8(ST[2 * P], ST[2 * P + 1]);
;         f32x4 ws[4], qs[4];
;         bf16x8 fa[8];
; #pragma unroll
;         for (int tt = 0; tt < 4; ++tt) {
; #pragma unroll
;             for (int P = 0; P < 4; ++P) { fa[P] = *(const LAS bf16x8*)(B + SC_W + (16 * tt + fr) * 272 + (32 * P + 8 * fq) * 2);
;                                           fa[4 + P] = *(const LAS bf16x8*)(B + SC_QS + (16 * tt + fr) * 272 + (32 * P + 8 * fq) * 2); }
;             __builtin_amdgcn_sched_barrier(0);
;             ws[tt] = (f32x4){0.f, 0.f, 0.f, 0.f}; qs[tt] = (f32x4){0.f, 0.f, 0.f, 0.f};
; #pragma unroll
;             for (int P = 0; P < 4; ++P) { ws[tt] = mfma16(fa[P], Sb[P], ws[tt]); qs[tt] = mfma16(fa[4 + P], Sb[P], qs[tt]); }
;             __builtin_amdgcn_sched_barrier(0);
;         }
.Lsc_body:
	v_mov_b64_e32 v[50:51], v[2:3]
	v_mov_b64_e32 v[48:49], v[0:1]
	v_lshl_add_u64 v[2:3], s[50:51], 0, v[154:155]
	v_add_co_u32_e32 v2, vcc, s15, v2
	v_mov_b64_e32 v[62:63], v[14:15]
	v_mov_b64_e32 v[58:59], v[10:11]
	v_mov_b64_e32 v[54:55], v[6:7]
	s_add_i32 s16, s5, 1
	v_lshl_add_u64 v[0:1], s[50:51], 0, v[156:157]
	v_addc_co_u32_e32 v3, vcc, 0, v3, vcc
	v_mov_b64_e32 v[60:61], v[12:13]
	v_mov_b64_e32 v[56:57], v[8:9]
	v_mov_b64_e32 v[52:53], v[4:5]
	v_mov_b64_e32 v[202:203], v[118:119]
	v_mov_b64_e32 v[158:159], v[116:117]
	v_mov_b64_e32 v[66:67], v[114:115]
	v_mov_b64_e32 v[64:65], v[112:113]
	global_load_dwordx2 v[118:119], v[0:1], off offset:-64
	global_load_dwordx2 v[116:117], v[0:1], off offset:-32
	global_load_dwordx2 v[114:115], v[0:1], off
	global_load_dwordx2 v[112:113], v[0:1], off offset:32
	s_add_u32 s18, s50, s4
	global_load_dwordx4 v[12:15], v[2:3], off offset:2304
	global_load_dwordx4 v[8:11], v[2:3], off offset:2368
	global_load_dwordx4 v[4:7], v[2:3], off offset:2432
	s_nop 0
	global_load_dwordx4 v[0:3], v[2:3], off offset:2496
	s_addc_u32 s19, s51, s14
	v_mov_b32_e32 v120, v165
	global_load_dword v165, v121, s[18:19]
	s_bitcmp1_b32 s5, 0
	s_cselect_b32 s5, 0xf400, 0
	s_add_i32 s5, s5, 0
	v_add_u32_e32 v171, s5, v163
	v_add_u32_e32 v108, v171, v169
	ds_read_b128 v[80:83], v108
	ds_read_b128 v[84:87], v108 offset:64
	ds_read_b128 v[88:91], v108 offset:17408
	ds_read_b128 v[92:95], v108 offset:17472
	ds_read_b128 v[96:99], v108 offset:128
	ds_read_b128 v[100:103], v108 offset:192
	ds_read_b128 v[104:107], v108 offset:17536
	ds_read_b128 v[108:111], v108 offset:17600
	v_cvt_pk_bf16_f32 v68, v28, v29
	v_cvt_pk_bf16_f32 v69, v30, v31
	v_cvt_pk_bf16_f32 v70, v24, v25
	v_cvt_pk_bf16_f32 v71, v26, v27
	v_cvt_pk_bf16_f32 v72, v20, v21
	v_cvt_pk_bf16_f32 v73, v22, v23
	v_cvt_pk_bf16_f32 v74, v16, v17
	v_cvt_pk_bf16_f32 v75, v18, v19
	v_cvt_pk_bf16_f32 v76, v44, v45
	v_cvt_pk_bf16_f32 v77, v46, v47
	v_cvt_pk_bf16_f32 v78, v40, v41
	v_cvt_pk_bf16_f32 v79, v42, v43
	v_cvt_pk_bf16_f32 v172, v36, v37
	v_cvt_pk_bf16_f32 v173, v38, v39
	v_cvt_pk_bf16_f32 v174, v32, v33
	v_cvt_pk_bf16_f32 v175, v34, v35
	v_add_u32_e32 v246, v171, v168
	ds_read_b128 v[210:213], v246
	ds_read_b128 v[214:217], v246 offset:64
	ds_read_b128 v[218:221], v246 offset:17408
	ds_read_b128 v[222:225], v246 offset:17472
	ds_read_b128 v[226:229], v246 offset:128
	ds_read_b128 v[230:233], v246 offset:192
	ds_read_b128 v[234:237], v246 offset:17536
	ds_read_b128 v[238:241], v246 offset:17600
	s_waitcnt lgkmcnt(8)
	v_mfma_f32_16x16x32_bf16 v[80:83], v[80:83], v[68:71], 0
	v_mfma_f32_16x16x32_bf16 v[88:91], v[88:91], v[68:71], 0
	v_mfma_f32_16x16x32_bf16 v[80:83], v[84:87], v[72:75], v[80:83]
	v_mfma_f32_16x16x32_bf16 v[84:87], v[92:95], v[72:75], v[88:91]
	v_mfma_f32_16x16x32_bf16 v[80:83], v[96:99], v[76:79], v[80:83]
	v_mfma_f32_16x16x32_bf16 v[84:87], v[104:107], v[76:79], v[84:87]
	v_mfma_f32_16x16x32_bf16 v[176:179], v[100:103], v[172:175], v[80:83]
	v_mfma_f32_16x16x32_bf16 v[104:107], v[108:111], v[172:175], v[84:87]
	v_add_u32_e32 v185, v171, v167
	s_nop 7
	ds_read_b128 v[80:83], v185
	ds_read_b128 v[84:87], v185 offset:64
	ds_read_b128 v[88:91], v185 offset:17408
	ds_read_b128 v[92:95], v185 offset:17472
	ds_read_b128 v[96:99], v185 offset:128
	ds_read_b128 v[100:103], v185 offset:192
	ds_read_b128 v[108:111], v185 offset:17536
	ds_read_b128 v[190:193], v185 offset:17600
	s_waitcnt lgkmcnt(8)
	v_mfma_f32_16x16x32_bf16 v[210:213], v[210:213], v[68:71], 0
	v_mfma_f32_16x16x32_bf16 v[218:221], v[218:221], v[68:71], 0
	v_mfma_f32_16x16x32_bf16 v[210:213], v[214:217], v[72:75], v[210:213]
	v_mfma_f32_16x16x32_bf16 v[214:217], v[222:225], v[72:75], v[218:221]
	v_mfma_f32_16x16x32_bf16 v[210:213], v[226:229], v[76:79], v[210:213]
	v_mfma_f32_16x16x32_bf16 v[214:217], v[234:237], v[76:79], v[214:217]
	v_mfma_f32_16x16x32_bf16 v[186:189], v[230:233], v[172:175], v[210:213]
	v_mfma_f32_16x16x32_bf16 v[180:183], v[238:241], v[172:175], v[214:217]
	v_add_u32_e32 v247, v171, v166
	s_nop 7
	ds_read_b128 v[210:213], v247
	ds_read_b128 v[214:217], v247 offset:64
	ds_read_b128 v[218:221], v247 offset:17408
	ds_read_b128 v[222:225], v247 offset:17472
	ds_read_b128 v[226:229], v247 offset:128
	ds_read_b128 v[230:233], v247 offset:192
	ds_read_b128 v[234:237], v247 offset:17536
	ds_read_b128 v[238:241], v247 offset:17600
	s_waitcnt lgkmcnt(8)
	v_mfma_f32_16x16x32_bf16 v[80:83], v[80:83], v[68:71], 0
	v_mfma_f32_16x16x32_bf16 v[88:91], v[88:91], v[68:71], 0
	v_mfma_f32_16x16x32_bf16 v[80:83], v[84:87], v[72:75], v[80:83]
	v_mfma_f32_16x16x32_bf16 v[84:87], v[92:95], v[72:75], v[88:91]
	v_mfma_f32_16x16x32_bf16 v[80:83], v[96:99], v[76:79], v[80:83]
	v_mfma_f32_16x16x32_bf16 v[84:87], v[108:111], v[76:79], v[84:87]
	v_mfma_f32_16x16x32_bf16 v[194:197], v[100:103], v[172:175], v[80:83]
	v_mfma_f32_16x16x32_bf16 v[100:103], v[190:193], v[172:175], v[84:87]
	s_waitcnt lgkmcnt(0)
; #define LAS __attribute__((address_space(3)))
; __device__ __forceinline__ float bf2f(short b) { return __uint_as_float(((unsigned)(unsigned short)b) << 16); }
; __device__ __forceinline__ f32x4 mfma16(const bf16x8& a, const bf16x8& b, const f32x4& c) { return __builtin_amdgcn_mfma_f32_16x16x32_bf16(a, b, c, 0, 0, 0); }
; template <bool PROMPT>
; __device__ __forceinline__ void scan_block(const Params& p, LAS unsigned char* lds, int chs0, int nsteps, const float* s0, float* sfin, int rowbase, int ntok, int h, int half) {
;     ...
;         for (int tt = 0; tt < 4; ++tt) {
; #pragma unroll
;             for (int P = 0; P < 4; ++P) { fa[P] = *(const LAS bf16x8*)(B + SC_W + (16 * tt + fr) * 272 + (32 * P + 8 * fq) * 2);
;                                           fa[4 + P] = *(const LAS bf16x8*)(B + SC_QS + (16 * tt + fr) * 272 + (32 * P + 8 * fq) * 2); }
;             __builtin_amdgcn_sched_barrier(0);
;             ws[tt] = (f32x4){0.f, 0.f, 0.f, 0.f}; qs[tt] = (f32x4){0.f, 0.f, 0.f, 0.f};
; #pragma unroll
;             for (int P = 0; P < 4; ++P) { ws[tt] = mfma16(fa[P], Sb[P], ws[tt]); qs[tt] = mfma16(fa[4 + P], Sb[P], qs[tt]); }
;             __builtin_amdgcn_sched_barrier(0);
;         }
;         bf16x8 fq_[8], fk[8];
; #pragma unroll
;         for (int tt = 0; tt < 4; ++tt)
; #pragma unroll
;             for (int u = 0; u < 2; ++u) fq_[tt * 2 + u] = *(const LAS bf16x8*)(B + SC_QK + (16 * tt + fr) * 144 + (32 * u + 8 * fq) * 2);
;         __builtin_amdgcn_sched_barrier(0);
;         f32x4 vn[4], vd[4];
; #pragma unroll
;         for (int tt = 0; tt < 4; ++tt)
; #pragma unroll
;             for (int jj = 0; jj < 4; ++jj) { vn[tt][jj] = bf2f(u4[tt][jj]) - ws[tt][jj]; vd[tt][jj] = vn[tt][jj] * __expf(Glc - g4[tt][jj]); }
	v_mfma_f32_16x16x32_bf16 v[210:213], v[210:213], v[68:71], 0
	v_mfma_f32_16x16x32_bf16 v[218:221], v[218:221], v[68:71], 0
	v_mfma_f32_16x16x32_bf16 v[210:213], v[214:217], v[72:75], v[210:213]
	v_mfma_f32_16x16x32_bf16 v[214:217], v[222:225], v[72:75], v[218:221]
	v_mfma_f32_16x16x32_bf16 v[210:213], v[226:229], v[76:79], v[210:213]
	v_mfma_f32_16x16x32_bf16 v[214:217], v[234:237], v[76:79], v[214:217]
	v_mfma_f32_16x16x32_bf16 v[190:193], v[230:233], v[172:175], v[210:213]
	v_mfma_f32_16x16x32_bf16 v[108:111], v[238:241], v[172:175], v[214:217]
	v_add_u32_e32 v171, v171, v164
	s_nop 3
	ds_read_b128 v[68:71], v171 offset:53248
	ds_read_b128 v[72:75], v171 offset:53312
	ds_read_b128 v[76:79], v171 offset:55552
	ds_read_b128 v[80:83], v171 offset:55616
	ds_read_b128 v[84:87], v171 offset:57856
	ds_read_b128 v[88:91], v171 offset:57920
	ds_read_b128 v[92:95], v171 offset:60160
	ds_read_b128 v[96:99], v171 offset:60224
	v_sub_f32_e32 v172, v120, v60
	v_sub_f32_e32 v173, v120, v61
	v_mul_f32_e32 v172, 0x3fb8aa3b, v172
	v_mul_f32_e32 v173, 0x3fb8aa3b, v173
	v_exp_f32_e32 v172, v172
	v_exp_f32_e32 v173, v173
	v_and_b32_e32 v175, 0xffff0000, v202
	v_lshlrev_b32_e32 v174, 16, v202
	v_pk_add_f32 v[174:175], v[174:175], v[176:177] neg_lo:[0,1] neg_hi:[0,1]
	v_and_b32_e32 v199, 0xffff0000, v203
	v_pk_mul_f32 v[176:177], v[172:173], v[174:175]
	v_sub_f32_e32 v172, v120, v62
	v_sub_f32_e32 v173, v120, v63
	v_mul_f32_e32 v172, 0x3fb8aa3b, v172
	v_mul_f32_e32 v173, 0x3fb8aa3b, v173
	v_exp_f32_e32 v172, v172
	v_exp_f32_e32 v173, v173
	v_lshlrev_b32_e32 v198, 16, v203
	v_pk_add_f32 v[178:179], v[198:199], v[178:179] neg_lo:[0,1] neg_hi:[0,1]
	v_and_b32_e32 v201, 0xffff0000, v158
	v_pk_mul_f32 v[198:199], v[172:173], v[178:179]
	v_sub_f32_e32 v172, v120, v56
	v_sub_f32_e32 v173, v120, v57
	v_mul_f32_e32 v172, 0x3fb8aa3b, v172
	v_mul_f32_e32 v173, 0x3fb8aa3b, v173
	v_exp_f32_e32 v172, v172
	v_exp_f32_e32 v173, v173
	v_lshlrev_b32_e32 v200, 16, v158
	v_sub_f32_e32 v158, v120, v58
	v_pk_add_f32 v[186:187], v[200:201], v[186:187] neg_lo:[0,1] neg_hi:[0,1]
	v_mul_f32_e32 v158, 0x3fb8aa3b, v158
	v_pk_mul_f32 v[200:201], v[172:173], v[186:187]
	v_exp_f32_e32 v172, v158
	v_sub_f32_e32 v158, v120, v59
	v_mul_f32_e32 v158, 0x3fb8aa3b, v158
	v_exp_f32_e32 v173, v158
	v_and_b32_e32 v203, 0xffff0000, v159
	v_lshlrev_b32_e32 v202, 16, v159
	v_pk_add_f32 v[158:159], v[202:203], v[188:189] neg_lo:[0,1] neg_hi:[0,1]
	v_and_b32_e32 v203, 0xffff0000, v66
	v_pk_mul_f32 v[188:189], v[172:173], v[158:159]
	v_sub_f32_e32 v172, v120, v52
	v_sub_f32_e32 v173, v120, v53
	v_mul_f32_e32 v172, 0x3fb8aa3b, v172
	v_mul_f32_e32 v173, 0x3fb8aa3b, v173
	v_exp_f32_e32 v172, v172
	v_exp_f32_e32 v173, v173
	v_lshlrev_b32_e32 v202, 16, v66
	v_sub_f32_e32 v66, v120, v54
	v_pk_add_f32 v[194:195], v[202:203], v[194:195] neg_lo:[0,1] neg_hi:[0,1]
	v_mul_f32_e32 v66, 0x3fb8aa3b, v66
	v_pk_mul_f32 v[202:203], v[172:173], v[194:195]
	v_exp_f32_e32 v172, v66
	v_sub_f32_e32 v66, v120, v55
	v_mul_f32_e32 v66, 0x3fb8aa3b, v66
	v_exp_f32_e32 v173, v66
	v_and_b32_e32 v205, 0xffff0000, v67
	v_lshlrev_b32_e32 v204, 16, v67
	v_pk_add_f32 v[66:67], v[204:205], v[196:197] neg_lo:[0,1] neg_hi:[0,1]
	v_and_b32_e32 v205, 0xffff0000, v64
	v_pk_mul_f32 v[196:197], v[172:173], v[66:67]
	v_sub_f32_e32 v172, v120, v48
	v_sub_f32_e32 v173, v120, v49
	v_mul_f32_e32 v172, 0x3fb8aa3b, v172
	v_mul_f32_e32 v173, 0x3fb8aa3b, v173
	v_exp_f32_e32 v172, v172
	v_exp_f32_e32 v173, v173
	v_lshlrev_b32_e32 v204, 16, v64
	v_sub_f32_e32 v64, v120, v50
	v_pk_add_f32 v[190:191], v[204:205], v[190:191] neg_lo:[0,1] neg_hi:[0,1]
	v_mul_f32_e32 v64, 0x3fb8aa3b, v64
	v_pk_mul_f32 v[204:205], v[172:173], v[190:191]
	v_exp_f32_e32 v172, v64
	v_sub_f32_e32 v64, v120, v51
	v_mul_f32_e32 v64, 0x3fb8aa3b, v64
	v_exp_f32_e32 v173, v64
	v_mul_f32_e32 v60, 0x3fb8aa3b, v60
	v_mul_f32_e32 v61, 0x3fb8aa3b, v61
	v_and_b32_e32 v207, 0xffff0000, v65
	v_lshlrev_b32_e32 v206, 16, v65
	v_exp_f32_e32 v60, v60
	v_exp_f32_e32 v61, v61
	v_mul_f32_e32 v54, 0x3fb8aa3b, v54
	v_mul_f32_e32 v55, 0x3fb8aa3b, v55
	v_pk_add_f32 v[64:65], v[206:207], v[192:193] neg_lo:[0,1] neg_hi:[0,1]
	v_mul_f32_e32 v56, 0x3fb8aa3b, v56
	v_exp_f32_e32 v54, v54
	v_exp_f32_e32 v55, v55
	v_pk_mul_f32 v[192:193], v[172:173], v[64:65]
	v_cvt_pk_bf16_f32 v172, v174, v175
	v_cvt_pk_bf16_f32 v175, v158, v159
	v_mul_f32_e32 v62, 0x3fb8aa3b, v62
	v_mul_f32_e32 v63, 0x3fb8aa3b, v63
	v_exp_f32_e32 v158, v56
	v_mul_f32_e32 v56, 0x3fb8aa3b, v57
	v_mul_f32_e32 v57, 0x3fb8aa3b, v58
	v_cvt_pk_bf16_f32 v173, v178, v179
	v_cvt_pk_bf16_f32 v179, v188, v189
	v_cvt_pk_bf16_f32 v188, v190, v191
	v_exp_f32_e32 v62, v62
	v_exp_f32_e32 v63, v63
	v_exp_f32_e32 v190, v57
	v_mul_f32_e32 v57, 0x3fb8aa3b, v59
	v_mul_f32_e32 v52, 0x3fb8aa3b, v52
	v_exp_f32_e32 v191, v57
	v_exp_f32_e32 v159, v56
	v_pk_mul_f32 v[56:57], v[60:61], v[104:105]
	v_exp_f32_e32 v104, v52
	v_mul_f32_e32 v52, 0x3fb8aa3b, v53
	v_mul_f32_e32 v50, 0x3fb8aa3b, v50
	v_exp_f32_e32 v105, v52
	v_pk_mul_f32 v[52:53], v[54:55], v[102:103]
	v_exp_f32_e32 v54, v50
	v_mul_f32_e32 v50, 0x3fb8aa3b, v51
	v_exp_f32_e32 v55, v50
	v_mul_f32_e32 v50, 0x3fb8aa3b, v120
	v_pk_mul_f32 v[58:59], v[62:63], v[106:107]
	v_mul_f32_e32 v48, 0x3fb8aa3b, v48
	v_mul_f32_e32 v49, 0x3fb8aa3b, v49
	v_exp_f32_e32 v106, v50
	v_exp_f32_e32 v48, v48
	v_exp_f32_e32 v49, v49
	v_cvt_pk_bf16_f32 v174, v186, v187
	v_pk_mul_f32 v[30:31], v[30:31], v[106:107] op_sel_hi:[1,0]
	v_pk_mul_f32 v[28:29], v[28:29], v[106:107] op_sel_hi:[1,0]
	v_pk_mul_f32 v[26:27], v[26:27], v[106:107] op_sel_hi:[1,0]
	v_pk_mul_f32 v[24:25], v[24:25], v[106:107] op_sel_hi:[1,0]
; #define LAS __attribute__((address_space(3)))
; __device__ __forceinline__ bf16_t f2bf(float f) { return (bf16_t)(cvt_pk_bf16(f, 0.f) & 0xffffu); }
; template <bool PROMPT>
; __device__ __forceinline__ void scan_block(const Params& p, LAS unsigned char* lds, int chs0, int nsteps, const float* s0, float* sfin, int rowbase, int ntok, int h, int half) {
;     ...
;             for (int jj = 0; jj < 4; ++jj) o[tt][jj] = qs[tt][jj] * __expf(g4[tt][jj]);
;         const float gt = __expf(Glc);
; #pragma unroll
;         for (int T = 0; T < 8; ++T) ST[T] = ST[T] * gt;
;         __builtin_amdgcn_sched_barrier(0);
; #pragma unroll
;         for (int T = 0; T < 4; ++T)
; #pragma unroll
;             for (int u = 0; u < 2; ++u) fk[T * 2 + u] = *(const LAS bf16x8*)(B + SC_KT + (16 * T + fr) * 144 + (32 * u + 8 * fq) * 2);
;         __builtin_amdgcn_sched_barrier(0);
; #pragma unroll
;         for (int tt = 0; tt < 4; ++tt)
; #pragma unroll
;             for (int u = 0; u < 2; ++u) o[tt] = mfma16(fq_[tt * 2 + u], Vb[u], o[tt]);
;         __builtin_amdgcn_sched_barrier(0);
; #pragma unroll
;         for (int T = 0; T < 4; ++T)
; #pragma unroll
;             for (int u = 0; u < 2; ++u) fq_[T * 2 + u] = *(const LAS bf16x8*)(B + SC_KT + (16 * (4 + T) + fr) * 144 + (32 * u + 8 * fq) * 2);
;         __builtin_amdgcn_sched_barrier(0);
; #pragma unroll
;         for (int T = 0; T < 4; ++T)
; #pragma unroll
;             for (int u = 0; u < 2; ++u) ST[T] = mfma16(fk[T * 2 + u], Vd[u], ST[T]);
;         __builtin_amdgcn_sched_barrier(0);
; #pragma unroll
;         for (int T = 0; T < 4; ++T)
; #pragma unroll
;             for (int u = 0; u < 2; ++u) ST[4 + T] = mfma16(fq_[T * 2 + u], Vd[u], ST[4 + T]);
; #pragma unroll
;         for (int tt = 0; tt < 4; ++tt)
; #pragma unroll
;             for (int jj = 0; jj < 4; ++jj) {
;                 const int tok = 16 * tt + 4 * fq + jj;
;                 if constexpr (PROMPT) {
;                     const unsigned row = (unsigned)(rowbase + n * 64 + tok);
;                     CAT[row * (unsigned)DM + (unsigned)(512 + h * 128 + dv)] = f2bf(o[tt][jj]);
;                 } else {
;                     const unsigned row = (unsigned)(rowbase + n * 64 + (tok < ntok ? tok : 0));
;                     if (tok < ntok) CAT[row * (unsigned)DM + (unsigned)(512 + h * 128 + dv)] = f2bf(o[tt][jj]);
;                 }
;             }
;         SC_BAR();
	v_pk_mul_f32 v[22:23], v[22:23], v[106:107] op_sel_hi:[1,0]
	v_pk_mul_f32 v[20:21], v[20:21], v[106:107] op_sel_hi:[1,0]
	v_pk_mul_f32 v[18:19], v[18:19], v[106:107] op_sel_hi:[1,0]
	v_pk_mul_f32 v[16:17], v[16:17], v[106:107] op_sel_hi:[1,0]
	v_pk_mul_f32 v[46:47], v[46:47], v[106:107] op_sel_hi:[1,0]
	v_pk_mul_f32 v[44:45], v[44:45], v[106:107] op_sel_hi:[1,0]
	v_pk_mul_f32 v[42:43], v[42:43], v[106:107] op_sel_hi:[1,0]
	v_pk_mul_f32 v[40:41], v[40:41], v[106:107] op_sel_hi:[1,0]
	v_pk_mul_f32 v[38:39], v[38:39], v[106:107] op_sel_hi:[1,0]
	v_pk_mul_f32 v[36:37], v[36:37], v[106:107] op_sel_hi:[1,0]
	v_pk_mul_f32 v[34:35], v[34:35], v[106:107] op_sel_hi:[1,0]
	v_pk_mul_f32 v[32:33], v[32:33], v[106:107] op_sel_hi:[1,0]
	v_cvt_pk_bf16_f32 v176, v176, v177
	v_cvt_pk_bf16_f32 v177, v198, v199
	v_cvt_pk_bf16_f32 v178, v200, v201
	v_cvt_pk_bf16_f32 v186, v194, v195
	v_cvt_pk_bf16_f32 v187, v66, v67
	v_cvt_pk_bf16_f32 v189, v64, v65
	v_cvt_pk_bf16_f32 v64, v202, v203
	v_cvt_pk_bf16_f32 v65, v196, v197
	v_cvt_pk_bf16_f32 v66, v204, v205
	v_cvt_pk_bf16_f32 v67, v192, v193
	v_pk_mul_f32 v[62:63], v[190:191], v[182:183]
	v_pk_mul_f32 v[60:61], v[158:159], v[180:181]
	v_pk_mul_f32 v[50:51], v[104:105], v[100:101]
	v_pk_mul_f32 v[102:103], v[54:55], v[110:111]
	v_pk_mul_f32 v[100:101], v[48:49], v[108:109]
	ds_read_b128 v[104:107], v171 offset:34816
	ds_read_b128 v[108:111], v171 offset:34880
	ds_read_b128 v[180:183], v171 offset:37120
	ds_read_b128 v[190:193], v171 offset:37184
	ds_read_b128 v[194:197], v171 offset:39424
	ds_read_b128 v[198:201], v171 offset:39488
	ds_read_b128 v[202:205], v171 offset:41728
	ds_read_b128 v[206:209], v171 offset:41792
	s_waitcnt lgkmcnt(14)
	v_mfma_f32_16x16x32_bf16 v[54:57], v[68:71], v[172:175], v[56:59]
	s_waitcnt lgkmcnt(13)
	v_mfma_f32_16x16x32_bf16 v[58:61], v[76:79], v[172:175], v[60:63]
	s_waitcnt lgkmcnt(11)
	v_mfma_f32_16x16x32_bf16 v[48:51], v[84:87], v[172:175], v[50:53]
	s_waitcnt lgkmcnt(9)
	v_mfma_f32_16x16x32_bf16 v[68:71], v[92:95], v[172:175], v[100:103]
	v_mfma_f32_16x16x32_bf16 v[54:57], v[72:75], v[186:189], v[54:57]
	v_mfma_f32_16x16x32_bf16 v[58:61], v[80:83], v[186:189], v[58:61]
	v_mfma_f32_16x16x32_bf16 v[48:51], v[88:91], v[186:189], v[48:51]
	s_waitcnt lgkmcnt(8)
	v_mfma_f32_16x16x32_bf16 v[68:71], v[96:99], v[186:189], v[68:71]
	ds_read_b128 v[72:75], v171 offset:44032
	ds_read_b128 v[76:79], v171 offset:44096
	ds_read_b128 v[80:83], v171 offset:46336
	ds_read_b128 v[84:87], v171 offset:46400
	ds_read_b128 v[88:91], v171 offset:48640
	ds_read_b128 v[92:95], v171 offset:48704
	ds_read_b128 v[96:99], v171 offset:50944
	ds_read_b128 v[100:103], v171 offset:51008
	s_waitcnt lgkmcnt(14)
	v_mfma_f32_16x16x32_bf16 v[28:31], v[104:107], v[176:179], v[28:31]
	s_waitcnt lgkmcnt(13)
	v_mfma_f32_16x16x32_bf16 v[24:27], v[180:183], v[176:179], v[24:27]
	s_waitcnt lgkmcnt(11)
	v_mfma_f32_16x16x32_bf16 v[20:23], v[194:197], v[176:179], v[20:23]
	s_waitcnt lgkmcnt(9)
	v_mfma_f32_16x16x32_bf16 v[16:19], v[202:205], v[176:179], v[16:19]
	v_mfma_f32_16x16x32_bf16 v[28:31], v[108:111], v[64:67], v[28:31]
	v_mfma_f32_16x16x32_bf16 v[24:27], v[190:193], v[64:67], v[24:27]
	v_mfma_f32_16x16x32_bf16 v[20:23], v[198:201], v[64:67], v[20:23]
	s_waitcnt lgkmcnt(8)
	v_mfma_f32_16x16x32_bf16 v[16:19], v[206:209], v[64:67], v[16:19]
	s_waitcnt lgkmcnt(7)
	v_mfma_f32_16x16x32_bf16 v[44:47], v[72:75], v[176:179], v[44:47]
	v_cvt_pk_bf16_f32 v104, v54, s0
	v_cvt_pk_bf16_f32 v110, v50, s0
	s_waitcnt lgkmcnt(5)
	v_mfma_f32_16x16x32_bf16 v[40:43], v[80:83], v[176:179], v[40:43]
	v_cvt_pk_bf16_f32 v120, v68, s0
	v_cvt_pk_bf16_f32 v158, v69, s0
	s_waitcnt lgkmcnt(3)
	v_mfma_f32_16x16x32_bf16 v[36:39], v[88:91], v[176:179], v[36:39]
	v_cvt_pk_bf16_f32 v105, v55, s0
	s_waitcnt lgkmcnt(1)
	v_mfma_f32_16x16x32_bf16 v[32:35], v[96:99], v[176:179], v[32:35]
	v_cvt_pk_bf16_f32 v106, v56, s0
	v_cvt_pk_bf16_f32 v107, v57, s0
	v_cvt_pk_bf16_f32 v108, v58, s0
	v_cvt_pk_bf16_f32 v109, v59, s0
	v_cvt_pk_bf16_f32 v96, v60, s0
	v_cvt_pk_bf16_f32 v97, v61, s0
	v_cvt_pk_bf16_f32 v98, v48, s0
	v_cvt_pk_bf16_f32 v99, v49, s0
	v_cvt_pk_bf16_f32 v111, v51, s0
	v_cvt_pk_bf16_f32 v159, v70, s0
	v_cvt_pk_bf16_f32 v171, v71, s0
	global_store_short v152, v104, s[96:97]
	global_store_short v150, v105, s[96:97]
	global_store_short v148, v106, s[96:97]
	global_store_short v146, v107, s[96:97]
	global_store_short v144, v108, s[96:97]
	global_store_short v142, v109, s[96:97]
	global_store_short v140, v96, s[96:97]
	global_store_short v138, v97, s[96:97]
	global_store_short v136, v98, s[96:97]
	global_store_short v134, v99, s[96:97]
	v_mfma_f32_16x16x32_bf16 v[44:47], v[76:79], v[64:67], v[44:47]
	global_store_short v132, v110, s[96:97]
	global_store_short v130, v111, s[96:97]
	global_store_short v128, v120, s[96:97]
	global_store_short v126, v158, s[96:97]
	global_store_short v124, v159, s[96:97]
	global_store_short v122, v171, s[96:97]
	s_add_u32 s4, s4, 0x100
	v_mfma_f32_16x16x32_bf16 v[40:43], v[84:87], v[64:67], v[40:43]
	s_waitcnt lgkmcnt(0)
	s_barrier
	v_mfma_f32_16x16x32_bf16 v[36:39], v[92:95], v[64:67], v[36:39]
	s_addc_u32 s14, s14, 0
	s_add_u32 s96, s96, s6
	s_addc_u32 s97, s97, s7
	s_waitcnt lgkmcnt(0)
	v_mfma_f32_16x16x32_bf16 v[32:35], v[100:103], v[64:67], v[32:35]
	v_lshl_add_u64 v[154:155], v[154:155], 0, s[8:9]
	v_lshl_add_u64 v[156:157], v[156:157], 0, s[10:11]
	s_cmp_eq_u32 s16, 31
	s_mov_b32 s5, s16
	s_cbranch_scc0 .LBB0_602
; #define LAS __attribute__((address_space(3)))
; __device__ __forceinline__ f32x4 mfma16(const bf16x8& a, const bf16x8& b, const f32x4& c) { return __builtin_amdgcn_mfma_f32_16x16x32_bf16(a, b, c, 0, 0, 0); }
; template <bool PROMPT>
; __device__ __forceinline__ void scan_block(const Params& p, LAS unsigned char* lds, int chs0, int nsteps, const float* s0, float* sfin, int rowbase, int ntok, int h, int half) {
;     ...
;         const LAS unsigned char* B = lds + (n & 1) * SC_BUF;
;         bf16x8 Sb[4];
; #pragma unroll
;         for (int P = 0; P < 4; ++P) Sb[P] = pack8(ST[2 * P], ST[2 * P + 1]);
;         f32x4 ws[4], qs[4];
;         bf16x8 fa[8];
; #pragma unroll
;         for (int tt = 0; tt < 4; ++tt) {
; #pragma unroll
;             for (int P = 0; P < 4; ++P) { fa[P] = *(const LAS bf16x8*)(B + SC_W + (16 * tt + fr) * 272 + (32 * P + 8 * fq) * 2);
;                                           fa[4 + P] = *(const LAS bf16x8*)(B + SC_QS + (16 * tt + fr) * 272 + (32 * P + 8 * fq) * 2); }
;             __builtin_amdgcn_sched_barrier(0);
;             ws[tt] = (f32x4){0.f, 0.f, 0.f, 0.f}; qs[tt] = (f32x4){0.f, 0.f, 0.f, 0.f};
; #pragma unroll
;             for (int P = 0; P < 4; ++P) { ws[tt] = mfma16(fa[P], Sb[P], ws[tt]); qs[tt] = mfma16(fa[4 + P], Sb[P], qs[tt]); }
;             __builtin_amdgcn_sched_barrier(0);
;         }
;         bf16x8 fq_[8], fk[8];
; #pragma unroll
;         for (int tt = 0; tt < 4; ++tt)
; #pragma unroll
;             for (int u = 0; u < 2; ++u) fq_[tt * 2 + u] = *(const LAS bf16x8*)(B + SC_QK + (16 * tt + fr) * 144 + (32 * u + 8 * fq) * 2);
	s_lshl_b32 s4, s33, 8
	s_and_b32 s4, s4, 0x3800
	s_lshl_b32 s0, s0, 16
	s_add_u32 s0, s48, s0
	v_or_b32_e32 v48, s1, v160
	s_addc_u32 s1, s49, 0
	v_or_b32_e32 v132, s4, v170
	s_add_u32 s4, s0, 0x4300000
	v_lshlrev_b32_e32 v133, 1, v48
	s_addc_u32 s5, s1, 0
	s_add_i32 s0, 0, 0x13800
	v_add3_u32 v124, 0, v169, v163
	v_add3_u32 v88, s0, v169, v163
	ds_read_b128 v[60:63], v124 offset:62464
	ds_read_b128 v[64:67], v124 offset:62528
	ds_read_b128 v[68:71], v88
	ds_read_b128 v[72:75], v88 offset:64
	ds_read_b128 v[76:79], v124 offset:62592
	ds_read_b128 v[80:83], v124 offset:62656
	ds_read_b128 v[84:87], v88 offset:128
	ds_read_b128 v[88:91], v88 offset:192
	v_cvt_pk_bf16_f32 v48, v28, v29
	v_cvt_pk_bf16_f32 v49, v30, v31
	v_cvt_pk_bf16_f32 v50, v24, v25
	v_cvt_pk_bf16_f32 v51, v26, v27
	v_cvt_pk_bf16_f32 v52, v20, v21
	v_cvt_pk_bf16_f32 v53, v22, v23
	v_cvt_pk_bf16_f32 v54, v16, v17
	v_cvt_pk_bf16_f32 v55, v18, v19
	v_cvt_pk_bf16_f32 v56, v44, v45
	v_cvt_pk_bf16_f32 v57, v46, v47
	v_cvt_pk_bf16_f32 v58, v40, v41
	v_cvt_pk_bf16_f32 v59, v42, v43
	v_cvt_pk_bf16_f32 v92, v36, v37
	v_cvt_pk_bf16_f32 v93, v38, v39
	v_cvt_pk_bf16_f32 v94, v32, v33
	v_cvt_pk_bf16_f32 v95, v34, v35
	s_waitcnt lgkmcnt(7)
	v_mfma_f32_16x16x32_bf16 v[60:63], v[60:63], v[48:51], 0
	s_waitcnt lgkmcnt(5)
	v_mfma_f32_16x16x32_bf16 v[68:71], v[68:71], v[48:51], 0
	v_mfma_f32_16x16x32_bf16 v[60:63], v[64:67], v[52:55], v[60:63]
	s_waitcnt lgkmcnt(4)
	v_mfma_f32_16x16x32_bf16 v[64:67], v[72:75], v[52:55], v[68:71]
	s_waitcnt lgkmcnt(3)
	v_mfma_f32_16x16x32_bf16 v[60:63], v[76:79], v[56:59], v[60:63]
	s_waitcnt lgkmcnt(1)
	v_mfma_f32_16x16x32_bf16 v[64:67], v[84:87], v[56:59], v[64:67]
	v_mfma_f32_16x16x32_bf16 v[96:99], v[80:83], v[92:95], v[60:63]
	s_waitcnt lgkmcnt(0)
	v_mfma_f32_16x16x32_bf16 v[84:87], v[88:91], v[92:95], v[64:67]
	v_add_u32_e32 v80, 0x1100, v124
	v_add3_u32 v100, s0, v168, v163
	s_nop 0
	ds_read_b128 v[60:63], v80 offset:62464
	s_nop 0
	ds_read_b128 v[64:67], v80 offset:62528
	ds_read_b128 v[68:71], v100
	ds_read_b128 v[72:75], v100 offset:64
	ds_read_b128 v[76:79], v80 offset:62592
	ds_read_b128 v[80:83], v80 offset:62656
	ds_read_b128 v[88:91], v100 offset:128
	ds_read_b128 v[100:103], v100 offset:192
	s_waitcnt lgkmcnt(7)
	v_mfma_f32_16x16x32_bf16 v[60:63], v[60:63], v[48:51], 0
	s_waitcnt lgkmcnt(5)
	v_mfma_f32_16x16x32_bf16 v[68:71], v[68:71], v[48:51], 0
	v_mfma_f32_16x16x32_bf16 v[60:63], v[64:67], v[52:55], v[60:63]
	s_waitcnt lgkmcnt(4)
	v_mfma_f32_16x16x32_bf16 v[64:67], v[72:75], v[52:55], v[68:71]
	s_waitcnt lgkmcnt(3)
	v_mfma_f32_16x16x32_bf16 v[60:63], v[76:79], v[56:59], v[60:63]
	s_waitcnt lgkmcnt(1)
	v_mfma_f32_16x16x32_bf16 v[64:67], v[88:91], v[56:59], v[64:67]
	v_mfma_f32_16x16x32_bf16 v[104:107], v[80:83], v[92:95], v[60:63]
	s_waitcnt lgkmcnt(0)
	v_mfma_f32_16x16x32_bf16 v[100:103], v[100:103], v[92:95], v[64:67]
	v_add_u32_e32 v80, 0x2200, v124
	v_add3_u32 v108, s0, v167, v163
	s_nop 0
	ds_read_b128 v[60:63], v80 offset:62464
	s_nop 0
	ds_read_b128 v[64:67], v80 offset:62528
	ds_read_b128 v[68:71], v108
	ds_read_b128 v[72:75], v108 offset:64
	ds_read_b128 v[76:79], v80 offset:62592
	ds_read_b128 v[80:83], v80 offset:62656
	ds_read_b128 v[88:91], v108 offset:128
	ds_read_b128 v[108:111], v108 offset:192
	s_waitcnt lgkmcnt(7)
	v_mfma_f32_16x16x32_bf16 v[60:63], v[60:63], v[48:51], 0
	s_waitcnt lgkmcnt(5)
	v_mfma_f32_16x16x32_bf16 v[68:71], v[68:71], v[48:51], 0
	v_mfma_f32_16x16x32_bf16 v[60:63], v[64:67], v[52:55], v[60:63]
	s_waitcnt lgkmcnt(4)
	v_mfma_f32_16x16x32_bf16 v[64:67], v[72:75], v[52:55], v[68:71]
	s_waitcnt lgkmcnt(3)
	v_mfma_f32_16x16x32_bf16 v[60:63], v[76:79], v[56:59], v[60:63]
	s_waitcnt lgkmcnt(1)
	v_mfma_f32_16x16x32_bf16 v[64:67], v[88:91], v[56:59], v[64:67]
	v_mfma_f32_16x16x32_bf16 v[120:123], v[80:83], v[92:95], v[60:63]
	s_waitcnt lgkmcnt(0)
	v_mfma_f32_16x16x32_bf16 v[80:83], v[108:111], v[92:95], v[64:67]
	v_add_u32_e32 v88, 0x3300, v124
	v_add3_u32 v124, s0, v166, v163
	s_nop 0
	ds_read_b128 v[60:63], v88 offset:62464
	s_nop 0
	ds_read_b128 v[64:67], v88 offset:62528
	ds_read_b128 v[68:71], v124
	ds_read_b128 v[72:75], v124 offset:64
	ds_read_b128 v[76:79], v88 offset:62592
	ds_read_b128 v[88:91], v88 offset:62656
	ds_read_b128 v[108:111], v124 offset:128
	ds_read_b128 v[124:127], v124 offset:192
	s_waitcnt lgkmcnt(7)
	v_mfma_f32_16x16x32_bf16 v[60:63], v[60:63], v[48:51], 0
	s_waitcnt lgkmcnt(5)
	v_mfma_f32_16x16x32_bf16 v[48:51], v[68:71], v[48:51], 0
	v_mfma_f32_16x16x32_bf16 v[60:63], v[64:67], v[52:55], v[60:63]
	s_waitcnt lgkmcnt(4)
	v_mfma_f32_16x16x32_bf16 v[48:51], v[72:75], v[52:55], v[48:51]
	s_waitcnt lgkmcnt(3)
	v_mfma_f32_16x16x32_bf16 v[52:55], v[76:79], v[56:59], v[60:63]
	s_waitcnt lgkmcnt(1)
	v_mfma_f32_16x16x32_bf16 v[48:51], v[108:111], v[56:59], v[48:51]
	v_mfma_f32_16x16x32_bf16 v[108:111], v[88:91], v[92:95], v[52:55]
	s_waitcnt lgkmcnt(0)
	v_mfma_f32_16x16x32_bf16 v[88:91], v[124:127], v[92:95], v[48:51]
	s_add_i32 s0, 0, 0x1c400
	v_add3_u32 v76, s0, v163, v164
	s_nop 2
	ds_read_b128 v[48:51], v76
	ds_read_b128 v[52:55], v76 offset:64
	ds_read_b128 v[56:59], v76 offset:2304
	ds_read_b128 v[60:63], v76 offset:2368
	ds_read_b128 v[64:67], v76 offset:4608
	ds_read_b128 v[68:71], v76 offset:4672
	ds_read_b128 v[72:75], v76 offset:6912
	ds_read_b128 v[76:79], v76 offset:6976
	s_waitcnt vmcnt(16)
; #define LAS __attribute__((address_space(3)))
; __device__ __forceinline__ float bf2f(short b) { return __uint_as_float(((unsigned)(unsigned short)b) << 16); }
; template <bool PROMPT>
; __device__ __forceinline__ void scan_block(const Params& p, LAS unsigned char* lds, int chs0, int nsteps, const float* s0, float* sfin, int rowbase, int ntok, int h, int half) {
;     ...
;             for (int jj = 0; jj < 4; ++jj) { vn[tt][jj] = bf2f(u4[tt][jj]) - ws[tt][jj]; vd[tt][jj] = vn[tt][jj] * __expf(Glc - g4[tt][jj]); }
;         bf16x8 Vb[2], Vd[2];
; #pragma unroll
;         for (int u = 0; u < 2; ++u) { Vb[u] = pack8(vn[2 * u], vn[2 * u + 1]); Vd[u] = pack8(vd[2 * u], vd[2 * u + 1]); }
;         f32x4 o[4];
; #pragma unroll
;         for (int tt = 0; tt < 4; ++tt)
; #pragma unroll
;             for (int jj = 0; jj < 4; ++jj) o[tt][jj] = qs[tt][jj] * __expf(g4[tt][jj]);
;         const float gt = __expf(Glc);
; #pragma unroll
;         for (int T = 0; T < 8; ++T) ST[T] = ST[T] * gt;
;         __builtin_amdgcn_sched_barrier(0);
; #pragma unroll
;         for (int T = 0; T < 4; ++T)
; #pragma unroll
;             for (int u = 0; u < 2; ++u) fk[T * 2 + u] = *(const LAS bf16x8*)(B + SC_KT + (16 * T + fr) * 144 + (32 * u + 8 * fq) * 2);
	v_sub_f32_e32 v92, v165, v12
	v_sub_f32_e32 v93, v165, v13
	v_mul_f32_e32 v92, 0x3fb8aa3b, v92
	v_mul_f32_e32 v93, 0x3fb8aa3b, v93
	v_exp_f32_e32 v92, v92
	v_exp_f32_e32 v93, v93
	v_and_b32_e32 v95, 0xffff0000, v118
	v_lshlrev_b32_e32 v94, 16, v118
	v_pk_add_f32 v[94:95], v[94:95], v[96:97] neg_lo:[0,1] neg_hi:[0,1]
	v_and_b32_e32 v125, 0xffff0000, v119
	v_pk_mul_f32 v[96:97], v[92:93], v[94:95]
	v_sub_f32_e32 v92, v165, v14
	v_sub_f32_e32 v93, v165, v15
	v_mul_f32_e32 v92, 0x3fb8aa3b, v92
	v_mul_f32_e32 v93, 0x3fb8aa3b, v93
	v_exp_f32_e32 v92, v92
	v_exp_f32_e32 v93, v93
	v_lshlrev_b32_e32 v124, 16, v119
	v_pk_add_f32 v[98:99], v[124:125], v[98:99] neg_lo:[0,1] neg_hi:[0,1]
	v_and_b32_e32 v125, 0xffff0000, v116
	v_pk_mul_f32 v[118:119], v[92:93], v[98:99]
	v_sub_f32_e32 v92, v165, v8
	v_sub_f32_e32 v93, v165, v9
	v_mul_f32_e32 v92, 0x3fb8aa3b, v92
	v_mul_f32_e32 v93, 0x3fb8aa3b, v93
	v_exp_f32_e32 v92, v92
	v_exp_f32_e32 v93, v93
	v_lshlrev_b32_e32 v124, 16, v116
	v_pk_add_f32 v[104:105], v[124:125], v[104:105] neg_lo:[0,1] neg_hi:[0,1]
	v_and_b32_e32 v127, 0xffff0000, v117
	v_pk_mul_f32 v[124:125], v[92:93], v[104:105]
	v_sub_f32_e32 v92, v165, v10
	v_sub_f32_e32 v93, v165, v11
	v_mul_f32_e32 v92, 0x3fb8aa3b, v92
	v_mul_f32_e32 v93, 0x3fb8aa3b, v93
	v_exp_f32_e32 v92, v92
	v_exp_f32_e32 v93, v93
	v_lshlrev_b32_e32 v126, 16, v117
	v_pk_add_f32 v[106:107], v[126:127], v[106:107] neg_lo:[0,1] neg_hi:[0,1]
	v_and_b32_e32 v127, 0xffff0000, v114
	v_pk_mul_f32 v[116:117], v[92:93], v[106:107]
	v_sub_f32_e32 v92, v165, v4
	v_sub_f32_e32 v93, v165, v5
	v_mul_f32_e32 v92, 0x3fb8aa3b, v92
	v_mul_f32_e32 v93, 0x3fb8aa3b, v93
	v_exp_f32_e32 v92, v92
	v_exp_f32_e32 v93, v93
	v_lshlrev_b32_e32 v126, 16, v114
	v_pk_add_f32 v[120:121], v[126:127], v[120:121] neg_lo:[0,1] neg_hi:[0,1]
	v_and_b32_e32 v129, 0xffff0000, v115
	v_pk_mul_f32 v[126:127], v[92:93], v[120:121]
	v_sub_f32_e32 v92, v165, v6
	v_sub_f32_e32 v93, v165, v7
	v_mul_f32_e32 v92, 0x3fb8aa3b, v92
	v_mul_f32_e32 v93, 0x3fb8aa3b, v93
	v_exp_f32_e32 v92, v92
	v_exp_f32_e32 v93, v93
	v_lshlrev_b32_e32 v128, 16, v115
	v_pk_add_f32 v[114:115], v[128:129], v[122:123] neg_lo:[0,1] neg_hi:[0,1]
	v_and_b32_e32 v129, 0xffff0000, v112
	v_pk_mul_f32 v[122:123], v[92:93], v[114:115]
	v_sub_f32_e32 v92, v165, v0
	v_sub_f32_e32 v93, v165, v1
	v_mul_f32_e32 v92, 0x3fb8aa3b, v92
	v_mul_f32_e32 v93, 0x3fb8aa3b, v93
	v_exp_f32_e32 v92, v92
	v_exp_f32_e32 v93, v93
	v_lshlrev_b32_e32 v128, 16, v112
	v_pk_add_f32 v[108:109], v[128:129], v[108:109] neg_lo:[0,1] neg_hi:[0,1]
	v_and_b32_e32 v131, 0xffff0000, v113
	v_pk_mul_f32 v[128:129], v[92:93], v[108:109]
	v_sub_f32_e32 v92, v165, v2
	v_sub_f32_e32 v93, v165, v3
	v_mul_f32_e32 v92, 0x3fb8aa3b, v92
	v_mul_f32_e32 v93, 0x3fb8aa3b, v93
	v_exp_f32_e32 v92, v92
	v_exp_f32_e32 v93, v93
	v_lshlrev_b32_e32 v130, 16, v113
	v_mul_f32_e32 v12, 0x3fb8aa3b, v12
	v_mul_f32_e32 v13, 0x3fb8aa3b, v13
	v_pk_add_f32 v[110:111], v[130:131], v[110:111] neg_lo:[0,1] neg_hi:[0,1]
	v_exp_f32_e32 v12, v12
	v_exp_f32_e32 v13, v13
	v_mul_f32_e32 v6, 0x3fb8aa3b, v6
	v_mul_f32_e32 v7, 0x3fb8aa3b, v7
	v_pk_mul_f32 v[112:113], v[92:93], v[110:111]
	v_mul_f32_e32 v8, 0x3fb8aa3b, v8
	v_exp_f32_e32 v6, v6
	v_exp_f32_e32 v7, v7
	v_cvt_pk_bf16_f32 v92, v94, v95
	v_cvt_pk_bf16_f32 v95, v106, v107
	v_cvt_pk_bf16_f32 v107, v110, v111
	v_cvt_pk_bf16_f32 v111, v112, v113
	v_mul_f32_e32 v14, 0x3fb8aa3b, v14
	v_mul_f32_e32 v15, 0x3fb8aa3b, v15
	v_exp_f32_e32 v112, v8
	v_mul_f32_e32 v8, 0x3fb8aa3b, v9
	v_mul_f32_e32 v9, 0x3fb8aa3b, v10
	v_cvt_pk_bf16_f32 v94, v104, v105
	v_cvt_pk_bf16_f32 v105, v114, v115
	v_exp_f32_e32 v14, v14
	v_exp_f32_e32 v15, v15
	v_exp_f32_e32 v114, v9
	v_mul_f32_e32 v9, 0x3fb8aa3b, v11
	v_mul_f32_e32 v4, 0x3fb8aa3b, v4
	v_exp_f32_e32 v115, v9
	v_exp_f32_e32 v113, v8
	v_pk_mul_f32 v[8:9], v[12:13], v[84:85]
	v_exp_f32_e32 v84, v4
	v_mul_f32_e32 v4, 0x3fb8aa3b, v5
	v_mul_f32_e32 v2, 0x3fb8aa3b, v2
	v_exp_f32_e32 v85, v4
	v_pk_mul_f32 v[4:5], v[6:7], v[82:83]
	v_exp_f32_e32 v6, v2
	v_mul_f32_e32 v2, 0x3fb8aa3b, v3
	v_mul_f32_e32 v0, 0x3fb8aa3b, v0
	v_mul_f32_e32 v1, 0x3fb8aa3b, v1
	v_exp_f32_e32 v7, v2
	v_mul_f32_e32 v2, 0x3fb8aa3b, v165
	v_pk_mul_f32 v[10:11], v[14:15], v[86:87]
	v_exp_f32_e32 v0, v0
	v_exp_f32_e32 v1, v1
	v_exp_f32_e32 v86, v2
	v_cvt_pk_bf16_f32 v93, v98, v99
	v_cvt_pk_bf16_f32 v96, v96, v97
	v_cvt_pk_bf16_f32 v97, v118, v119
	v_cvt_pk_bf16_f32 v98, v124, v125
	v_cvt_pk_bf16_f32 v99, v116, v117
	v_cvt_pk_bf16_f32 v104, v120, v121
	v_cvt_pk_bf16_f32 v106, v108, v109
	v_cvt_pk_bf16_f32 v108, v126, v127
	v_cvt_pk_bf16_f32 v109, v122, v123
	v_cvt_pk_bf16_f32 v110, v128, v129
	v_pk_mul_f32 v[14:15], v[114:115], v[102:103]
	v_pk_mul_f32 v[12:13], v[112:113], v[100:101]
	v_pk_mul_f32 v[2:3], v[84:85], v[80:81]
	v_pk_mul_f32 v[82:83], v[6:7], v[90:91]
	v_pk_mul_f32 v[80:81], v[0:1], v[88:89]
	v_pk_mul_f32 v[30:31], v[86:87], v[30:31] op_sel_hi:[0,1]
	v_pk_mul_f32 v[28:29], v[86:87], v[28:29] op_sel_hi:[0,1]
	v_pk_mul_f32 v[26:27], v[86:87], v[26:27] op_sel_hi:[0,1]
	v_pk_mul_f32 v[24:25], v[86:87], v[24:25] op_sel_hi:[0,1]
	v_pk_mul_f32 v[22:23], v[86:87], v[22:23] op_sel_hi:[0,1]
	v_pk_mul_f32 v[20:21], v[86:87], v[20:21] op_sel_hi:[0,1]
	v_pk_mul_f32 v[18:19], v[86:87], v[18:19] op_sel_hi:[0,1]
	v_pk_mul_f32 v[16:17], v[86:87], v[16:17] op_sel_hi:[0,1]
	v_pk_mul_f32 v[46:47], v[86:87], v[46:47] op_sel_hi:[0,1]
	v_pk_mul_f32 v[44:45], v[86:87], v[44:45] op_sel_hi:[0,1]
	v_pk_mul_f32 v[42:43], v[86:87], v[42:43] op_sel_hi:[0,1]
	v_pk_mul_f32 v[40:41], v[86:87], v[40:41] op_sel_hi:[0,1]
	v_pk_mul_f32 v[38:39], v[86:87], v[38:39] op_sel_hi:[0,1]
	v_pk_mul_f32 v[36:37], v[86:87], v[36:37] op_sel_hi:[0,1]
	v_pk_mul_f32 v[34:35], v[86:87], v[34:35] op_sel_hi:[0,1]
	v_pk_mul_f32 v[32:33], v[86:87], v[32:33] op_sel_hi:[0,1]
	s_add_i32 s0, 0, 0x17c00
	v_add3_u32 v0, s0, v163, v164
	ds_read_b128 v[84:87], v0
	ds_read_b128 v[88:91], v0 offset:64
	ds_read_b128 v[100:103], v0 offset:2304
	ds_read_b128 v[112:115], v0 offset:2368
	ds_read_b128 v[116:119], v0 offset:4608
	ds_read_b128 v[120:123], v0 offset:4672
	ds_read_b128 v[124:127], v0 offset:6912
	ds_read_b128 v[128:131], v0 offset:6976
	s_waitcnt lgkmcnt(14)
; #define LAS __attribute__((address_space(3)))
; __device__ __forceinline__ bf16_t f2bf(float f) { return (bf16_t)(cvt_pk_bf16(f, 0.f) & 0xffffu); }
; __device__ __forceinline__ f32x4 mfma16(const bf16x8& a, const bf16x8& b, const f32x4& c) { return __builtin_amdgcn_mfma_f32_16x16x32_bf16(a, b, c, 0, 0, 0); }
; template <bool PROMPT>
; __device__ __forceinline__ void scan_block(const Params& p, LAS unsigned char* lds, int chs0, int nsteps, const float* s0, float* sfin, int rowbase, int ntok, int h, int half) {
;     ...
; #pragma unroll
;         for (int tt = 0; tt < 4; ++tt)
; #pragma unroll
;             for (int u = 0; u < 2; ++u) o[tt] = mfma16(fq_[tt * 2 + u], Vb[u], o[tt]);
;         __builtin_amdgcn_sched_barrier(0);
; #pragma unroll
;         for (int T = 0; T < 4; ++T)
; #pragma unroll
;             for (int u = 0; u < 2; ++u) fq_[T * 2 + u] = *(const LAS bf16x8*)(B + SC_KT + (16 * (4 + T) + fr) * 144 + (32 * u + 8 * fq) * 2);
;         __builtin_amdgcn_sched_barrier(0);
; #pragma unroll
;         for (int T = 0; T < 4; ++T)
; #pragma unroll
;             for (int u = 0; u < 2; ++u) ST[T] = mfma16(fk[T * 2 + u], Vd[u], ST[T]);
;         __builtin_amdgcn_sched_barrier(0);
; #pragma unroll
;         for (int T = 0; T < 4; ++T)
; #pragma unroll
;             for (int u = 0; u < 2; ++u) ST[4 + T] = mfma16(fq_[T * 2 + u], Vd[u], ST[4 + T]);
; #pragma unroll
;         for (int tt = 0; tt < 4; ++tt)
; #pragma unroll
;             for (int jj = 0; jj < 4; ++jj) {
;                 const int tok = 16 * tt + 4 * fq + jj;
;                 if constexpr (PROMPT) {
;                     const unsigned row = (unsigned)(rowbase + n * 64 + tok);
;                     CAT[row * (unsigned)DM + (unsigned)(512 + h * 128 + dv)] = f2bf(o[tt][jj]);
;                 } else {
;                     const unsigned row = (unsigned)(rowbase + n * 64 + (tok < ntok ? tok : 0));
;                     if (tok < ntok) CAT[row * (unsigned)DM + (unsigned)(512 + h * 128 + dv)] = f2bf(o[tt][jj]);
;                 }
;             }
	v_mfma_f32_16x16x32_bf16 v[6:9], v[48:51], v[92:95], v[8:11]
	s_waitcnt lgkmcnt(13)
	v_mfma_f32_16x16x32_bf16 v[10:13], v[56:59], v[92:95], v[12:15]
	s_waitcnt lgkmcnt(11)
	v_mfma_f32_16x16x32_bf16 v[0:3], v[64:67], v[92:95], v[2:5]
	s_waitcnt lgkmcnt(9)
	v_mfma_f32_16x16x32_bf16 v[48:51], v[72:75], v[92:95], v[80:83]
	v_mfma_f32_16x16x32_bf16 v[6:9], v[52:55], v[104:107], v[6:9]
	v_mfma_f32_16x16x32_bf16 v[10:13], v[60:63], v[104:107], v[10:13]
	v_mfma_f32_16x16x32_bf16 v[0:3], v[68:71], v[104:107], v[0:3]
	s_waitcnt lgkmcnt(8)
	v_mfma_f32_16x16x32_bf16 v[48:51], v[76:79], v[104:107], v[48:51]
	s_add_i32 s0, 0, 0x1a000
	v_add3_u32 v4, s0, v163, v164
	ds_read_b128 v[52:55], v4
	ds_read_b128 v[56:59], v4 offset:64
	ds_read_b128 v[60:63], v4 offset:2304
	ds_read_b128 v[64:67], v4 offset:2368
	ds_read_b128 v[68:71], v4 offset:4608
	ds_read_b128 v[72:75], v4 offset:4672
	ds_read_b128 v[76:79], v4 offset:6912
	ds_read_b128 v[80:83], v4 offset:6976
	s_waitcnt lgkmcnt(14)
	v_mfma_f32_16x16x32_bf16 v[28:31], v[84:87], v[96:99], v[28:31]
	s_waitcnt lgkmcnt(13)
	v_mfma_f32_16x16x32_bf16 v[24:27], v[100:103], v[96:99], v[24:27]
	s_waitcnt lgkmcnt(11)
	v_mfma_f32_16x16x32_bf16 v[20:23], v[116:119], v[96:99], v[20:23]
	s_waitcnt lgkmcnt(9)
	v_mfma_f32_16x16x32_bf16 v[14:17], v[124:127], v[96:99], v[16:19]
	v_mfma_f32_16x16x32_bf16 v[28:31], v[88:91], v[108:111], v[28:31]
	v_mfma_f32_16x16x32_bf16 v[24:27], v[112:115], v[108:111], v[24:27]
	v_mfma_f32_16x16x32_bf16 v[20:23], v[120:123], v[108:111], v[20:23]
	s_waitcnt lgkmcnt(8)
	v_mfma_f32_16x16x32_bf16 v[14:17], v[128:131], v[108:111], v[14:17]
	v_cvt_pk_bf16_f32 v6, v6, s0
	v_lshlrev_b32_e32 v4, 11, v132
	s_movk_i32 s0, 0x400
	v_or3_b32 v18, v133, v4, s0
	v_mov_b32_e32 v19, 0
	s_waitcnt lgkmcnt(7)
	v_mfma_f32_16x16x32_bf16 v[44:47], v[52:55], v[96:99], v[44:47]
	v_lshl_add_u64 v[52:53], s[50:51], 0, v[18:19]
	s_mov_b32 s0, 0x9f20000
	v_add_co_u32_e32 v4, vcc, s0, v52
	s_mov_b32 s0, 0x9f21000
	s_nop 0
	v_addc_co_u32_e32 v5, vcc, 0, v53, vcc
	v_add_co_u32_e32 v54, vcc, s0, v52
	v_cvt_pk_bf16_f32 v8, v8, s0
	s_nop 0
	v_addc_co_u32_e32 v55, vcc, 0, v53, vcc
	global_store_short v[54:55], v6, off offset:-4096
	v_cvt_pk_bf16_f32 v6, v7, s0
	global_store_short v[54:55], v8, off
	v_cvt_pk_bf16_f32 v8, v9, s0
	v_cvt_pk_bf16_f32 v10, v10, s0
	s_mov_b32 s0, 0x9f28000
	global_store_short v[54:55], v8, off offset:2048
	v_add_co_u32_e32 v8, vcc, s0, v52
	s_mov_b32 s0, 0x9f29000
	s_nop 0
	v_addc_co_u32_e32 v9, vcc, 0, v53, vcc
	global_store_short v[4:5], v6, off offset:2048
	s_waitcnt lgkmcnt(1)
	v_mfma_f32_16x16x32_bf16 v[4:7], v[76:79], v[96:99], v[32:35]
	v_cvt_pk_bf16_f32 v0, v0, s0
	s_nop 1
	v_add_co_u32_e32 v32, vcc, s0, v52
	v_mfma_f32_16x16x32_bf16 v[44:47], v[56:59], v[108:111], v[44:47]
	s_nop 0
	v_addc_co_u32_e32 v33, vcc, 0, v53, vcc
	global_store_short v[32:33], v10, off offset:-4096
	v_cvt_pk_bf16_f32 v10, v11, s0
	global_store_short v[8:9], v10, off offset:2048
	v_cvt_pk_bf16_f32 v8, v12, s0
	global_store_short v[32:33], v8, off
	v_cvt_pk_bf16_f32 v8, v13, s0
	s_mov_b32 s0, 0x9f30000
	global_store_short v[32:33], v8, off offset:2048
	v_add_co_u32_e32 v8, vcc, s0, v52
	s_mov_b32 s0, 0x9f31000
	s_nop 0
	v_addc_co_u32_e32 v9, vcc, 0, v53, vcc
	v_add_co_u32_e32 v10, vcc, s0, v52
	v_mfma_f32_16x16x32_bf16 v[40:43], v[60:63], v[96:99], v[40:43]
	s_nop 0
	v_addc_co_u32_e32 v11, vcc, 0, v53, vcc
	global_store_short v[10:11], v0, off offset:-4096
	v_cvt_pk_bf16_f32 v0, v1, s0
	global_store_short v[8:9], v0, off offset:2048
	v_cvt_pk_bf16_f32 v0, v2, s0
	global_store_short v[10:11], v0, off
	v_cvt_pk_bf16_f32 v0, v3, s0
	v_cvt_pk_bf16_f32 v8, v48, s0
	s_mov_b32 s0, 0x9f38000
	global_store_short v[10:11], v0, off offset:2048
	v_add_co_u32_e32 v0, vcc, s0, v52
	s_mov_b32 s0, 0x9f39000
	s_nop 0
	v_addc_co_u32_e32 v1, vcc, 0, v53, vcc
	v_add_co_u32_e32 v2, vcc, s0, v52
	v_mfma_f32_16x16x32_bf16 v[36:39], v[68:71], v[96:99], v[36:39]
	s_nop 0
	v_addc_co_u32_e32 v3, vcc, 0, v53, vcc
	global_store_short v[2:3], v8, off offset:-4096
	v_cvt_pk_bf16_f32 v8, v49, s0
	global_store_short v[0:1], v8, off offset:2048
	v_cvt_pk_bf16_f32 v0, v50, s0
	global_store_short v[2:3], v0, off
	v_cvt_pk_bf16_f32 v0, v51, s0
	global_store_short v[2:3], v0, off offset:2048
	v_lshlrev_b32_e32 v0, 2, v160
	v_lshl_or_b32 v18, v162, 11, v0
	v_lshl_add_u64 v[0:1], s[4:5], 0, v[18:19]
	s_movk_i32 s0, 0x2000
	v_add_co_u32_e32 v2, vcc, s0, v0
	s_movk_i32 s0, 0x4000
	s_nop 0
	v_addc_co_u32_e32 v3, vcc, 0, v1, vcc
	s_waitcnt lgkmcnt(0)
	s_barrier
; __device__ __forceinline__ f32x4 mfma16(const bf16x8& a, const bf16x8& b, const f32x4& c) { return __builtin_amdgcn_mfma_f32_16x16x32_bf16(a, b, c, 0, 0, 0); }
; template <bool PROMPT>
; __device__ __forceinline__ void scan_block(const Params& p, LAS unsigned char* lds, int chs0, int nsteps, const float* s0, float* sfin, int rowbase, int ntok, int h, int half) {
;     ...
;         for (int T = 0; T < 4; ++T)
; #pragma unroll
;             for (int u = 0; u < 2; ++u) ST[4 + T] = mfma16(fq_[T * 2 + u], Vd[u], ST[4 + T]);
;     ...
;     for (int T = 0; T < 8; ++T)
; #pragma unroll
;         for (int jj = 0; jj < 4; ++jj) sfin[(size_t)(16 * T + 4 * fq + jj) * 128 + dv] = ST[T][jj];
	global_store_dword v18, v28, s[4:5]
	global_store_dword v18, v29, s[4:5] offset:512
	global_store_dword v18, v30, s[4:5] offset:1024
	global_store_dword v18, v31, s[4:5] offset:1536
	global_store_dword v[2:3], v24, off
	global_store_dword v[2:3], v25, off offset:512
	global_store_dword v[2:3], v26, off offset:1024
	global_store_dword v[2:3], v27, off offset:1536
	v_add_co_u32_e32 v2, vcc, s0, v0
	v_lshl_or_b32 v8, v161, 9, v160
	s_nop 0
	v_addc_co_u32_e32 v3, vcc, 0, v1, vcc
	v_or_b32_e32 v18, 0x1800, v8
	global_store_dword v[2:3], v20, off
	global_store_dword v[2:3], v21, off offset:512
	global_store_dword v[2:3], v22, off offset:1024
	global_store_dword v[2:3], v23, off offset:1536
	v_lshl_add_u64 v[2:3], v[18:19], 2, s[4:5]
	v_or_b32_e32 v18, 0x1880, v8
	global_store_dword v[2:3], v14, off
	v_lshl_add_u64 v[2:3], v[18:19], 2, s[4:5]
	v_or_b32_e32 v18, 0x1900, v8
	global_store_dword v[2:3], v15, off
	v_lshl_add_u64 v[2:3], v[18:19], 2, s[4:5]
	v_or_b32_e32 v18, 0x1980, v8
	global_store_dword v[2:3], v16, off
	v_lshl_add_u64 v[2:3], v[18:19], 2, s[4:5]
	s_mov_b32 s0, 0x8000
	global_store_dword v[2:3], v17, off
	v_add_co_u32_e32 v2, vcc, s0, v0
	s_mov_b32 s0, 0xa000
	s_nop 0
	v_addc_co_u32_e32 v3, vcc, 0, v1, vcc
	v_mfma_f32_16x16x32_bf16 v[40:43], v[64:67], v[108:111], v[40:43]
	global_store_dword v[2:3], v44, off
	global_store_dword v[2:3], v45, off offset:512
	global_store_dword v[2:3], v46, off offset:1024
	global_store_dword v[2:3], v47, off offset:1536
	v_add_co_u32_e32 v2, vcc, s0, v0
	v_mfma_f32_16x16x32_bf16 v[36:39], v[72:75], v[108:111], v[36:39]
	s_nop 0
	v_addc_co_u32_e32 v3, vcc, 0, v1, vcc
	s_mov_b32 s0, 0xc000
	s_waitcnt lgkmcnt(0)
	v_mfma_f32_16x16x32_bf16 v[4:7], v[80:83], v[108:111], v[4:7]
	v_add_co_u32_e32 v0, vcc, s0, v0
	v_or_b32_e32 v18, 0x3800, v8
	s_nop 0
	v_addc_co_u32_e32 v1, vcc, 0, v1, vcc
	global_store_dword v[2:3], v40, off
	global_store_dword v[2:3], v41, off offset:512
	global_store_dword v[2:3], v42, off offset:1024
	global_store_dword v[2:3], v43, off offset:1536
	global_store_dword v[0:1], v36, off
	global_store_dword v[0:1], v37, off offset:512
	global_store_dword v[0:1], v38, off offset:1024
	global_store_dword v[0:1], v39, off offset:1536
	v_lshl_add_u64 v[0:1], v[18:19], 2, s[4:5]
	v_or_b32_e32 v18, 0x3880, v8
	global_store_dword v[0:1], v4, off
	v_lshl_add_u64 v[0:1], v[18:19], 2, s[4:5]
	v_or_b32_e32 v18, 0x3900, v8
	global_store_dword v[0:1], v5, off
	v_lshl_add_u64 v[0:1], v[18:19], 2, s[4:5]
	v_or_b32_e32 v18, 0x3980, v8
	global_store_dword v[0:1], v6, off
	v_lshl_add_u64 v[0:1], v[18:19], 2, s[4:5]
	global_store_dword v[0:1], v7, off
